# speedup vs baseline: 1.0092x; 1.0092x over previous
; DEVI void lds_barrier() { asm volatile("s_waitcnt lgkmcnt(0)" ::: "memory"); __builtin_amdgcn_s_barrier(); asm volatile("" ::: "memory"); }
; DEVI void deferred_conv(const Params& p, char* smem, const int which) {
;   float* lds = (float*)smem;
;   int* qs = (int*)(smem + 40960);
;   unsigned* ctr = (unsigned*)(p.ws + O_CTR) + which * 16;
;   const int tlo = which ? DQ_WO + DQ_WUP : 0, thi = which ? DQ_TOTAL : DQ_WO + DQ_WUP;
;   char* ws = p.ws;
;   for (;;) {
;     if (threadIdx.x == 0) *qs = tlo + (int)atomicAdd(ctr, (unsigned)DQ_GRAB);
;     lds_barrier();
;     int base = *qs;
;     lds_barrier();
;     if (base >= thi) break;
;     TcPre R[DQ_GRAB];
; #pragma unroll
;     for (int u = 0; u < DQ_GRAB; ++u) {
;       int t = base + u;
;       if (t < thi) {
;         if (t < DQ_WO) tconv_load(p.w_o, 4096, t, R[u]);
;         else if (t < DQ_WO + DQ_WUP) tconv_load(p.w_up, NUP, t - DQ_WO, R[u]);
;         else tconv_load(p.w_down, 4096, t - DQ_WO - DQ_WUP, R[u]);
;       }
;     }
.LBB0_183:
	s_waitcnt lgkmcnt(0)
	s_barrier
	v_mov_b32_e32 v50, 0
	v_mov_b32_e32 v51, 4
	v_mov_b32_e32 v84, 0x10400
	v_lshrrev_b32_e32 v55, 5, v164
	v_and_b32_e32 v56, 31, v164
	v_lshlrev_b32_e32 v56, 4, v56
	v_lshrrev_b32_e32 v53, 3, v164
	v_and_b32_e32 v57, 7, v164
	v_lshlrev_b32_e32 v57, 4, v57
	s_mov_b32 s6, 0x2000
	v_mad_u32_u24 v57, v53, s6, v57
	s_movk_i32 s6, 0x204
	v_mad_u32_u24 v58, v55, s6, v56
	v_add_u32_e32 v59, 0x2040, v58
	v_add_u32_e32 v60, 0x4080, v58
	v_add_u32_e32 v61, 0x60c0, v58
	v_add_u32_e32 v62, 0x8100, v58
	v_add_u32_e32 v63, 0xa140, v58
	v_add_u32_e32 v64, 0xc180, v58
	v_add_u32_e32 v65, 0xe1c0, v58
	v_and_b32_e32 v66, 7, v164
	s_movk_i32 s6, 0x1020
	v_lshlrev_b32_e32 v53, 2, v53
	v_mad_u32_u24 v66, v66, s6, v53
	v_add_u32_e32 v67, 0x408, v66
	v_add_u32_e32 v68, 0x810, v66
	v_add_u32_e32 v69, 0xc18, v66
	v_add_u32_e32 v70, 0x100, v66
	v_add_u32_e32 v71, 0x508, v66
	v_add_u32_e32 v72, 0x910, v66
	v_add_u32_e32 v73, 0xd18, v66
	v_add_u32_e32 v74, 0x8100, v66
	v_add_u32_e32 v75, 0x8508, v66
	v_add_u32_e32 v76, 0x8910, v66
	v_add_u32_e32 v77, 0x8d18, v66
	v_add_u32_e32 v78, 0x8200, v66
	v_add_u32_e32 v79, 0x8608, v66
	v_add_u32_e32 v80, 0x8a10, v66
	v_add_u32_e32 v81, 0x8e18, v66
	s_add_u32 s10, s56, 0x2b403000
	s_addc_u32 s11, s57, 0
	v_readfirstlane_b32 s33, v164
	s_mov_b64 s[76:77], exec
	s_cmp_lg_u32 s33, 0
	s_cbranch_scc1 .Ldcv0_q0
	s_mov_b64 exec, 1
	global_atomic_add v82, v50, v51, s[10:11] sc0
	global_atomic_add v83, v50, v51, s[10:11] sc0
	s_waitcnt vmcnt(0)
	ds_write_b64 v84, v[82:83]
	s_mov_b64 exec, s[76:77]
.Ldcv0_q0:
	s_waitcnt lgkmcnt(0)
	s_barrier
	ds_read_b64 v[82:83], v84
	s_waitcnt lgkmcnt(0)
	v_readfirstlane_b32 s3, v82
	v_readfirstlane_b32 s4, v83
	s_cmp_ge_u32 s3, 0x3300
	s_cbranch_scc1 .Ldcv0_done
	s_cmp_lt_u32 s3, 0x800
	s_cbranch_scc0 .Ldcv0_sup_pro
	s_lshr_b32 s6, s3, 5
	s_and_b32 s7, s3, 31
	s_lshl_b32 s6, s6, 20
	s_lshl_b32 s7, s7, 9
	s_add_u32 s6, s6, s7
	s_add_u32 s68, s46, s6
	s_addc_u32 s69, s47, 0
	s_mov_b32 s70, 0x40000
	s_movk_i32 s88, 0x4000
	s_branch .Ldcv0_sdn_pro
.Ldcv0_sup_pro:
	s_sub_u32 s7, s3, 0x800
	s_mul_i32 s6, s7, 0xbe83
	s_lshr_b32 s6, s6, 23
	s_mul_i32 s15, s6, 0xac
	s_sub_u32 s7, s7, s15
	s_mul_i32 s6, s6, 0x560000
	s_lshl_b32 s7, s7, 9
	s_add_u32 s6, s6, s7
	s_add_u32 s68, s22, s6
	s_addc_u32 s69, s23, 0
	s_mov_b32 s70, 0x158000
	s_mov_b32 s88, 0x15800
.Ldcv0_sdn_pro:
	v_mad_u32_u24 v54, v55, s88, v56
	global_load_dwordx4 v[168:171], v54, s[68:69]
	s_add_u32 s68, s68, s70
	s_addc_u32 s69, s69, 0
	global_load_dwordx4 v[172:175], v54, s[68:69]
	s_add_u32 s68, s68, s70
	s_addc_u32 s69, s69, 0
	global_load_dwordx4 v[176:179], v54, s[68:69]
	s_add_u32 s68, s68, s70
	s_addc_u32 s69, s69, 0
	global_load_dwordx4 v[180:183], v54, s[68:69]
	s_mul_i32 s6, s70, 3
	s_sub_u32 s68, s68, s6
	s_subb_u32 s69, s69, 0
	s_add_u32 s68, s68, 0x200
	s_addc_u32 s69, s69, 0
	global_load_dwordx4 v[184:187], v54, s[68:69]
	s_add_u32 s68, s68, s70
	s_addc_u32 s69, s69, 0
	global_load_dwordx4 v[188:191], v54, s[68:69]
	s_add_u32 s68, s68, s70
	s_addc_u32 s69, s69, 0
	global_load_dwordx4 v[192:195], v54, s[68:69]
	s_add_u32 s68, s68, s70
	s_addc_u32 s69, s69, 0
	global_load_dwordx4 v[196:199], v54, s[68:69]
	s_mul_i32 s6, s70, 3
	s_sub_u32 s68, s68, s6
	s_subb_u32 s69, s69, 0
	s_add_u32 s68, s68, 0x200
	s_addc_u32 s69, s69, 0
	global_load_dwordx4 v[200:203], v54, s[68:69]
	s_add_u32 s68, s68, s70
	s_addc_u32 s69, s69, 0
	global_load_dwordx4 v[204:207], v54, s[68:69]
	s_add_u32 s68, s68, s70
	s_addc_u32 s69, s69, 0
	global_load_dwordx4 v[208:211], v54, s[68:69]
	s_add_u32 s68, s68, s70
	s_addc_u32 s69, s69, 0
	global_load_dwordx4 v[212:215], v54, s[68:69]
	s_mul_i32 s6, s70, 3
	s_sub_u32 s68, s68, s6
	s_subb_u32 s69, s69, 0
	s_add_u32 s68, s68, 0x200
	s_addc_u32 s69, s69, 0
	global_load_dwordx4 v[216:219], v54, s[68:69]
	s_add_u32 s68, s68, s70
	s_addc_u32 s69, s69, 0
	global_load_dwordx4 v[220:223], v54, s[68:69]
	s_add_u32 s68, s68, s70
	s_addc_u32 s69, s69, 0
	global_load_dwordx4 v[224:227], v54, s[68:69]
	s_add_u32 s68, s68, s70
	s_addc_u32 s69, s69, 0
	global_load_dwordx4 v[228:231], v54, s[68:69]
	s_mul_i32 s6, s70, 3
	s_sub_u32 s68, s68, s6
	s_subb_u32 s69, s69, 0
	s_add_u32 s68, s68, 0x200
	s_addc_u32 s69, s69, 0
	s_waitcnt vmcnt(0)
; DEVI unsigned pack2(float a, float b) { f32v2 v = {a, b}; return __builtin_bit_cast(unsigned, __builtin_convertvector(v, bf16v2)); }
; DEVI void lds_barrier() { asm volatile("s_waitcnt lgkmcnt(0)" ::: "memory"); __builtin_amdgcn_s_barrier(); asm volatile("" ::: "memory"); }
; DEVI void tconv_store(const TcPre& R, u16* __restrict__ Wt, int K, int N, int t, float* lds, bool perm) {
;   const int tid = threadIdx.x;
;   const int tnN = N / 128;
;   int tk = t / tnN, tn = t % tnN, k0 = tk * 64, n0 = tn * 128;
;   {
;     float* d = lds + (tid >> 5) * 129 + (tid & 31) * 4;
;     d[0] = R.a[0]; d[1] = R.a[1]; d[2] = R.a[2]; d[3] = R.a[3];
;     d[16 * 129] = R.b[0]; d[16 * 129 + 1] = R.b[1]; d[16 * 129 + 2] = R.b[2]; d[16 * 129 + 3] = R.b[3];
;     d[32 * 129] = R.c[0]; d[32 * 129 + 1] = R.c[1]; d[32 * 129 + 2] = R.c[2]; d[32 * 129 + 3] = R.c[3];
;     d[48 * 129] = R.d[0]; d[48 * 129 + 1] = R.d[1]; d[48 * 129 + 2] = R.d[2]; d[48 * 129 + 3] = R.d[3];
;   }
;   lds_barrier();
;   int n0p = !perm ? n0 : (n0 < DFF ? (n0 / 128) * 256 : ((n0 - DFF) / 128) * 256 + 128);
; #pragma unroll
;   for (int p = 0; p < 2; ++p) {
;     int item = p * 512 + tid, n = item >> 3, kg = item & 7;
;     const float* s = lds + (kg * 8) * 129 + n;
;     uint4 o;
;     o.x = pack2(s[0], s[129]); o.y = pack2(s[2 * 129], s[3 * 129]);
;     o.z = pack2(s[4 * 129], s[5 * 129]); o.w = pack2(s[6 * 129], s[7 * 129]);
;     *(uint4*)(Wt + (size_t)(n0p + n) * K + k0 + kg * 8) = o;
;   }
;   lds_barrier();
; }
; DEVI void deferred_conv(const Params& p, char* smem, const int which) {
;     ...
;   for (;;) {
;     if (threadIdx.x == 0) *qs = tlo + (int)atomicAdd(ctr, (unsigned)DQ_GRAB);
;     lds_barrier();
;     int base = *qs;
;     lds_barrier();
;     if (base >= thi) break;
;     TcPre R[DQ_GRAB];
; #pragma unroll
;     for (int u = 0; u < DQ_GRAB; ++u) {
;       int t = base + u;
;       if (t < thi) {
;         if (t < DQ_WO) tconv_load(p.w_o, 4096, t, R[u]);
;         else if (t < DQ_WO + DQ_WUP) tconv_load(p.w_up, NUP, t - DQ_WO, R[u]);
;         else tconv_load(p.w_down, 4096, t - DQ_WO - DQ_WUP, R[u]);
.Ldcv0_loop:
	s_cmp_ge_u32 s4, 0x3300
	s_cbranch_scc1 .Ldcv0_last
	s_cmp_lt_u32 s3, 0x800
	s_cbranch_scc0 .Ldcv0_dup_st
	s_lshr_b32 s6, s3, 5
	s_and_b32 s86, s3, 31
	s_lshl_b32 s6, s6, 7
	s_add_u32 s6, s6, 0xa800000
	s_mov_b32 s87, 0
	s_branch .Ldcv0_ddn_st
.Ldcv0_dup_st:
	s_sub_u32 s7, s3, 0x800
	s_mul_i32 s6, s7, 0xbe83
	s_lshr_b32 s6, s6, 23
	s_mul_i32 s15, s6, 0xac
	s_sub_u32 s86, s7, s15
	s_lshl_b32 s6, s6, 7
	s_add_u32 s6, s6, 0xc800000
	s_mov_b32 s87, 1
.Ldcv0_ddn_st:
	s_add_u32 s84, s56, s6
	s_addc_u32 s85, s57, 0
	s_cmp_lt_u32 s4, 0x800
	s_cbranch_scc0 .Ldcv0_sup_st
	s_lshr_b32 s6, s4, 5
	s_and_b32 s7, s4, 31
	s_lshl_b32 s6, s6, 20
	s_lshl_b32 s7, s7, 9
	s_add_u32 s6, s6, s7
	s_add_u32 s68, s46, s6
	s_addc_u32 s69, s47, 0
	s_mov_b32 s70, 0x40000
	s_movk_i32 s88, 0x4000
	s_branch .Ldcv0_sdn_st
.Ldcv0_sup_st:
	s_sub_u32 s7, s4, 0x800
	s_mul_i32 s6, s7, 0xbe83
	s_lshr_b32 s6, s6, 23
	s_mul_i32 s15, s6, 0xac
	s_sub_u32 s7, s7, s15
	s_mul_i32 s6, s6, 0x560000
	s_lshl_b32 s7, s7, 9
	s_add_u32 s6, s6, s7
	s_add_u32 s68, s22, s6
	s_addc_u32 s69, s23, 0
	s_mov_b32 s70, 0x158000
	s_mov_b32 s88, 0x15800
.Ldcv0_sdn_st:
	v_mad_u32_u24 v54, v55, s88, v56
	s_cmp_lg_u32 s33, 0
	s_cbranch_scc1 .Ldcv0_a_st
	s_mov_b64 exec, 1
	global_atomic_add v52, v50, v51, s[10:11] sc0
	s_mov_b64 exec, s[76:77]
.Ldcv0_a_st:
	s_add_u32 s6, s86, 0
	s_cmp_eq_u32 s87, 0
	s_cbranch_scc1 .Ldcv0_np_st0
	s_lshl_b32 s7, s6, 8
	s_sub_u32 s15, s7, 0x5580
	s_cmp_lt_u32 s6, 86
	s_cselect_b32 s6, s7, s15
	s_lshl_b32 s6, s6, 13
	s_branch .Ldcv0_npd_st0
.Ldcv0_np_st0:
	s_lshl_b32 s6, s6, 20
.Ldcv0_npd_st0:
	s_add_u32 s72, s84, s6
	s_addc_u32 s73, s85, 0
	s_add_u32 s78, s72, 0x80000
	s_addc_u32 s79, s73, 0
	s_waitcnt vmcnt(20)
	ds_write2_b32 v58, v168, v169 offset1:1
	ds_write2_b32 v58, v170, v171 offset0:2 offset1:3
	ds_write2_b32 v59, v172, v173 offset1:1
	ds_write2_b32 v59, v174, v175 offset0:2 offset1:3
	ds_write2_b32 v60, v176, v177 offset1:1
	ds_write2_b32 v60, v178, v179 offset0:2 offset1:3
	ds_write2_b32 v61, v180, v181 offset1:1
	ds_write2_b32 v61, v182, v183 offset0:2 offset1:3
	global_load_dwordx4 v[168:171], v54, s[68:69]
	s_add_u32 s68, s68, s70
	s_addc_u32 s69, s69, 0
	global_load_dwordx4 v[172:175], v54, s[68:69]
	s_add_u32 s68, s68, s70
	s_addc_u32 s69, s69, 0
	global_load_dwordx4 v[176:179], v54, s[68:69]
	s_add_u32 s68, s68, s70
	s_addc_u32 s69, s69, 0
	global_load_dwordx4 v[180:183], v54, s[68:69]
	s_mul_i32 s6, s70, 3
	s_sub_u32 s68, s68, s6
	s_subb_u32 s69, s69, 0
	s_add_u32 s68, s68, 0x200
	s_addc_u32 s69, s69, 0
	s_waitcnt lgkmcnt(0)
	s_barrier
	ds_read2_b32 v[104:105], v66 offset1:129
	ds_read2_b32 v[106:107], v67 offset1:129
	ds_read2_b32 v[108:109], v68 offset1:129
	ds_read2_b32 v[110:111], v69 offset1:129
	ds_read2_b32 v[112:113], v70 offset1:129
	ds_read2_b32 v[114:115], v71 offset1:129
	ds_read2_b32 v[116:117], v72 offset1:129
	ds_read2_b32 v[118:119], v73 offset1:129
	s_waitcnt lgkmcnt(4)
	v_cvt_pk_bf16_f32 v120, v104, v105
	v_cvt_pk_bf16_f32 v121, v106, v107
	v_cvt_pk_bf16_f32 v122, v108, v109
	v_cvt_pk_bf16_f32 v123, v110, v111
	global_store_dwordx4 v57, v[120:123], s[72:73]
	s_waitcnt lgkmcnt(0)
	v_cvt_pk_bf16_f32 v124, v112, v113
	v_cvt_pk_bf16_f32 v125, v114, v115
	v_cvt_pk_bf16_f32 v126, v116, v117
	v_cvt_pk_bf16_f32 v127, v118, v119
	global_store_dwordx4 v57, v[124:127], s[78:79]
	s_add_u32 s6, s86, 1
	s_cmp_eq_u32 s87, 0
	s_cbranch_scc1 .Ldcv0_np_st1
	s_lshl_b32 s7, s6, 8
	s_sub_u32 s15, s7, 0x5580
	s_cmp_lt_u32 s6, 86
	s_cselect_b32 s6, s7, s15
	s_lshl_b32 s6, s6, 13
	s_branch .Ldcv0_npd_st1

; DEVI unsigned pack2(float a, float b) { f32v2 v = {a, b}; return __builtin_bit_cast(unsigned, __builtin_convertvector(v, bf16v2)); }
; DEVI void lds_barrier() { asm volatile("s_waitcnt lgkmcnt(0)" ::: "memory"); __builtin_amdgcn_s_barrier(); asm volatile("" ::: "memory"); }
; DEVI void tconv_store(const TcPre& R, u16* __restrict__ Wt, int K, int N, int t, float* lds, bool perm) {
;   const int tid = threadIdx.x;
;   const int tnN = N / 128;
;   int tk = t / tnN, tn = t % tnN, k0 = tk * 64, n0 = tn * 128;
;   {
;     float* d = lds + (tid >> 5) * 129 + (tid & 31) * 4;
;     d[0] = R.a[0]; d[1] = R.a[1]; d[2] = R.a[2]; d[3] = R.a[3];
;     d[16 * 129] = R.b[0]; d[16 * 129 + 1] = R.b[1]; d[16 * 129 + 2] = R.b[2]; d[16 * 129 + 3] = R.b[3];
;     d[32 * 129] = R.c[0]; d[32 * 129 + 1] = R.c[1]; d[32 * 129 + 2] = R.c[2]; d[32 * 129 + 3] = R.c[3];
;     d[48 * 129] = R.d[0]; d[48 * 129 + 1] = R.d[1]; d[48 * 129 + 2] = R.d[2]; d[48 * 129 + 3] = R.d[3];
;   }
;   lds_barrier();
;   int n0p = !perm ? n0 : (n0 < DFF ? (n0 / 128) * 256 : ((n0 - DFF) / 128) * 256 + 128);
; #pragma unroll
;   for (int p = 0; p < 2; ++p) {
;     int item = p * 512 + tid, n = item >> 3, kg = item & 7;
;     const float* s = lds + (kg * 8) * 129 + n;
;     uint4 o;
;     o.x = pack2(s[0], s[129]); o.y = pack2(s[2 * 129], s[3 * 129]);
;     o.z = pack2(s[4 * 129], s[5 * 129]); o.w = pack2(s[6 * 129], s[7 * 129]);
;     *(uint4*)(Wt + (size_t)(n0p + n) * K + k0 + kg * 8) = o;
;   }
;   lds_barrier();
; }
.Ldcv0_npd_st1:
	s_add_u32 s72, s84, s6
	s_addc_u32 s73, s85, 0
	s_add_u32 s78, s72, 0x80000
	s_addc_u32 s79, s73, 0
	s_waitcnt vmcnt(20)
	ds_write2_b32 v62, v184, v185 offset1:1
	ds_write2_b32 v62, v186, v187 offset0:2 offset1:3
	ds_write2_b32 v63, v188, v189 offset1:1
	ds_write2_b32 v63, v190, v191 offset0:2 offset1:3
	ds_write2_b32 v64, v192, v193 offset1:1
	ds_write2_b32 v64, v194, v195 offset0:2 offset1:3
	ds_write2_b32 v65, v196, v197 offset1:1
	ds_write2_b32 v65, v198, v199 offset0:2 offset1:3
	global_load_dwordx4 v[184:187], v54, s[68:69]
	s_add_u32 s68, s68, s70
	s_addc_u32 s69, s69, 0
	global_load_dwordx4 v[188:191], v54, s[68:69]
	s_add_u32 s68, s68, s70
	s_addc_u32 s69, s69, 0
	global_load_dwordx4 v[192:195], v54, s[68:69]
	s_add_u32 s68, s68, s70
	s_addc_u32 s69, s69, 0
	global_load_dwordx4 v[196:199], v54, s[68:69]
	s_mul_i32 s6, s70, 3
	s_sub_u32 s68, s68, s6
	s_subb_u32 s69, s69, 0
	s_add_u32 s68, s68, 0x200
	s_addc_u32 s69, s69, 0
	s_waitcnt lgkmcnt(0)
	s_barrier
	ds_read2_b32 v[104:105], v74 offset1:129
	ds_read2_b32 v[106:107], v75 offset1:129
	ds_read2_b32 v[108:109], v76 offset1:129
	ds_read2_b32 v[110:111], v77 offset1:129
	ds_read2_b32 v[112:113], v78 offset1:129
	ds_read2_b32 v[114:115], v79 offset1:129
	ds_read2_b32 v[116:117], v80 offset1:129
	ds_read2_b32 v[118:119], v81 offset1:129
	s_waitcnt lgkmcnt(4)
	v_cvt_pk_bf16_f32 v120, v104, v105
	v_cvt_pk_bf16_f32 v121, v106, v107
	v_cvt_pk_bf16_f32 v122, v108, v109
	v_cvt_pk_bf16_f32 v123, v110, v111
	global_store_dwordx4 v57, v[120:123], s[72:73]
	s_waitcnt lgkmcnt(0)
	v_cvt_pk_bf16_f32 v124, v112, v113
	v_cvt_pk_bf16_f32 v125, v114, v115
	v_cvt_pk_bf16_f32 v126, v116, v117
	v_cvt_pk_bf16_f32 v127, v118, v119
	global_store_dwordx4 v57, v[124:127], s[78:79]
	s_add_u32 s6, s86, 2
	s_cmp_eq_u32 s87, 0
	s_cbranch_scc1 .Ldcv0_np_st2
	s_lshl_b32 s7, s6, 8
	s_sub_u32 s15, s7, 0x5580
	s_cmp_lt_u32 s6, 86
	s_cselect_b32 s6, s7, s15
	s_lshl_b32 s6, s6, 13
	s_branch .Ldcv0_npd_st2

; DEVI unsigned pack2(float a, float b) { f32v2 v = {a, b}; return __builtin_bit_cast(unsigned, __builtin_convertvector(v, bf16v2)); }
; DEVI void lds_barrier() { asm volatile("s_waitcnt lgkmcnt(0)" ::: "memory"); __builtin_amdgcn_s_barrier(); asm volatile("" ::: "memory"); }
; DEVI void tconv_store(const TcPre& R, u16* __restrict__ Wt, int K, int N, int t, float* lds, bool perm) {
;   const int tid = threadIdx.x;
;   const int tnN = N / 128;
;   int tk = t / tnN, tn = t % tnN, k0 = tk * 64, n0 = tn * 128;
;   {
;     float* d = lds + (tid >> 5) * 129 + (tid & 31) * 4;
;     d[0] = R.a[0]; d[1] = R.a[1]; d[2] = R.a[2]; d[3] = R.a[3];
;     d[16 * 129] = R.b[0]; d[16 * 129 + 1] = R.b[1]; d[16 * 129 + 2] = R.b[2]; d[16 * 129 + 3] = R.b[3];
;     d[32 * 129] = R.c[0]; d[32 * 129 + 1] = R.c[1]; d[32 * 129 + 2] = R.c[2]; d[32 * 129 + 3] = R.c[3];
;     d[48 * 129] = R.d[0]; d[48 * 129 + 1] = R.d[1]; d[48 * 129 + 2] = R.d[2]; d[48 * 129 + 3] = R.d[3];
;   }
;   lds_barrier();
;   int n0p = !perm ? n0 : (n0 < DFF ? (n0 / 128) * 256 : ((n0 - DFF) / 128) * 256 + 128);
; #pragma unroll
;   for (int p = 0; p < 2; ++p) {
;     int item = p * 512 + tid, n = item >> 3, kg = item & 7;
;     const float* s = lds + (kg * 8) * 129 + n;
;     uint4 o;
;     o.x = pack2(s[0], s[129]); o.y = pack2(s[2 * 129], s[3 * 129]);
;     o.z = pack2(s[4 * 129], s[5 * 129]); o.w = pack2(s[6 * 129], s[7 * 129]);
;     *(uint4*)(Wt + (size_t)(n0p + n) * K + k0 + kg * 8) = o;
;   }
;   lds_barrier();
; }
.Ldcv0_npd_st2:
	s_add_u32 s72, s84, s6
	s_addc_u32 s73, s85, 0
	s_add_u32 s78, s72, 0x80000
	s_addc_u32 s79, s73, 0
	s_waitcnt vmcnt(20)
	ds_write2_b32 v58, v200, v201 offset1:1
	ds_write2_b32 v58, v202, v203 offset0:2 offset1:3
	ds_write2_b32 v59, v204, v205 offset1:1
	ds_write2_b32 v59, v206, v207 offset0:2 offset1:3
	ds_write2_b32 v60, v208, v209 offset1:1
	ds_write2_b32 v60, v210, v211 offset0:2 offset1:3
	ds_write2_b32 v61, v212, v213 offset1:1
	ds_write2_b32 v61, v214, v215 offset0:2 offset1:3
	global_load_dwordx4 v[200:203], v54, s[68:69]
	s_add_u32 s68, s68, s70
	s_addc_u32 s69, s69, 0
	global_load_dwordx4 v[204:207], v54, s[68:69]
	s_add_u32 s68, s68, s70
	s_addc_u32 s69, s69, 0
	global_load_dwordx4 v[208:211], v54, s[68:69]
	s_add_u32 s68, s68, s70
	s_addc_u32 s69, s69, 0
	global_load_dwordx4 v[212:215], v54, s[68:69]
	s_mul_i32 s6, s70, 3
	s_sub_u32 s68, s68, s6
	s_subb_u32 s69, s69, 0
	s_add_u32 s68, s68, 0x200
	s_addc_u32 s69, s69, 0
	s_waitcnt lgkmcnt(0)
	s_barrier
	ds_read2_b32 v[104:105], v66 offset1:129
	ds_read2_b32 v[106:107], v67 offset1:129
	ds_read2_b32 v[108:109], v68 offset1:129
	ds_read2_b32 v[110:111], v69 offset1:129
	ds_read2_b32 v[112:113], v70 offset1:129
	ds_read2_b32 v[114:115], v71 offset1:129
	ds_read2_b32 v[116:117], v72 offset1:129
	ds_read2_b32 v[118:119], v73 offset1:129
	s_waitcnt lgkmcnt(4)
	v_cvt_pk_bf16_f32 v120, v104, v105
	v_cvt_pk_bf16_f32 v121, v106, v107
	v_cvt_pk_bf16_f32 v122, v108, v109
	v_cvt_pk_bf16_f32 v123, v110, v111
	global_store_dwordx4 v57, v[120:123], s[72:73]
	s_waitcnt lgkmcnt(0)
	v_cvt_pk_bf16_f32 v124, v112, v113
	v_cvt_pk_bf16_f32 v125, v114, v115
	v_cvt_pk_bf16_f32 v126, v116, v117
	v_cvt_pk_bf16_f32 v127, v118, v119
	global_store_dwordx4 v57, v[124:127], s[78:79]
	s_add_u32 s6, s86, 3
	s_cmp_eq_u32 s87, 0
	s_cbranch_scc1 .Ldcv0_np_st3
	s_lshl_b32 s7, s6, 8
	s_sub_u32 s15, s7, 0x5580
	s_cmp_lt_u32 s6, 86
	s_cselect_b32 s6, s7, s15
	s_lshl_b32 s6, s6, 13
	s_branch .Ldcv0_npd_st3

; DEVI unsigned pack2(float a, float b) { f32v2 v = {a, b}; return __builtin_bit_cast(unsigned, __builtin_convertvector(v, bf16v2)); }
; DEVI void lds_barrier() { asm volatile("s_waitcnt lgkmcnt(0)" ::: "memory"); __builtin_amdgcn_s_barrier(); asm volatile("" ::: "memory"); }
; DEVI void tconv_store(const TcPre& R, u16* __restrict__ Wt, int K, int N, int t, float* lds, bool perm) {
;   const int tid = threadIdx.x;
;   const int tnN = N / 128;
;   int tk = t / tnN, tn = t % tnN, k0 = tk * 64, n0 = tn * 128;
;   {
;     float* d = lds + (tid >> 5) * 129 + (tid & 31) * 4;
;     d[0] = R.a[0]; d[1] = R.a[1]; d[2] = R.a[2]; d[3] = R.a[3];
;     d[16 * 129] = R.b[0]; d[16 * 129 + 1] = R.b[1]; d[16 * 129 + 2] = R.b[2]; d[16 * 129 + 3] = R.b[3];
;     d[32 * 129] = R.c[0]; d[32 * 129 + 1] = R.c[1]; d[32 * 129 + 2] = R.c[2]; d[32 * 129 + 3] = R.c[3];
;     d[48 * 129] = R.d[0]; d[48 * 129 + 1] = R.d[1]; d[48 * 129 + 2] = R.d[2]; d[48 * 129 + 3] = R.d[3];
;   }
;   lds_barrier();
;   int n0p = !perm ? n0 : (n0 < DFF ? (n0 / 128) * 256 : ((n0 - DFF) / 128) * 256 + 128);
; #pragma unroll
;   for (int p = 0; p < 2; ++p) {
;     int item = p * 512 + tid, n = item >> 3, kg = item & 7;
;     const float* s = lds + (kg * 8) * 129 + n;
;     uint4 o;
;     o.x = pack2(s[0], s[129]); o.y = pack2(s[2 * 129], s[3 * 129]);
;     o.z = pack2(s[4 * 129], s[5 * 129]); o.w = pack2(s[6 * 129], s[7 * 129]);
;     *(uint4*)(Wt + (size_t)(n0p + n) * K + k0 + kg * 8) = o;
;   }
;   lds_barrier();
; }
; DEVI void deferred_conv(const Params& p, char* smem, const int which) {
;     ...
;   for (;;) {
;     if (threadIdx.x == 0) *qs = tlo + (int)atomicAdd(ctr, (unsigned)DQ_GRAB);
;     lds_barrier();
;     int base = *qs;
;     lds_barrier();
;     if (base >= thi) break;
.Ldcv0_npd_st3:
	s_add_u32 s72, s84, s6
	s_addc_u32 s73, s85, 0
	s_add_u32 s78, s72, 0x80000
	s_addc_u32 s79, s73, 0
	s_waitcnt vmcnt(20)
	ds_write2_b32 v62, v216, v217 offset1:1
	ds_write2_b32 v62, v218, v219 offset0:2 offset1:3
	ds_write2_b32 v63, v220, v221 offset1:1
	ds_write2_b32 v63, v222, v223 offset0:2 offset1:3
	ds_write2_b32 v64, v224, v225 offset1:1
	ds_write2_b32 v64, v226, v227 offset0:2 offset1:3
	ds_write2_b32 v65, v228, v229 offset1:1
	ds_write2_b32 v65, v230, v231 offset0:2 offset1:3
	global_load_dwordx4 v[216:219], v54, s[68:69]
	s_add_u32 s68, s68, s70
	s_addc_u32 s69, s69, 0
	global_load_dwordx4 v[220:223], v54, s[68:69]
	s_add_u32 s68, s68, s70
	s_addc_u32 s69, s69, 0
	global_load_dwordx4 v[224:227], v54, s[68:69]
	s_add_u32 s68, s68, s70
	s_addc_u32 s69, s69, 0
	global_load_dwordx4 v[228:231], v54, s[68:69]
	s_mul_i32 s6, s70, 3
	s_sub_u32 s68, s68, s6
	s_subb_u32 s69, s69, 0
	s_add_u32 s68, s68, 0x200
	s_addc_u32 s69, s69, 0
	s_cmp_lg_u32 s33, 0
	s_cbranch_scc1 .Ldcv0_b_st
	s_mov_b64 exec, 1
	s_waitcnt vmcnt(22)
	ds_write_b32 v84, v52
	s_mov_b64 exec, s[76:77]
.Ldcv0_b_st:
	s_waitcnt lgkmcnt(0)
	s_barrier
	ds_read2_b32 v[104:105], v74 offset1:129
	ds_read2_b32 v[106:107], v75 offset1:129
	ds_read2_b32 v[108:109], v76 offset1:129
	ds_read2_b32 v[110:111], v77 offset1:129
	ds_read2_b32 v[112:113], v78 offset1:129
	ds_read2_b32 v[114:115], v79 offset1:129
	ds_read2_b32 v[116:117], v80 offset1:129
	ds_read2_b32 v[118:119], v81 offset1:129
	ds_read_b32 v82, v84
	s_waitcnt lgkmcnt(5)
	v_cvt_pk_bf16_f32 v120, v104, v105
	v_cvt_pk_bf16_f32 v121, v106, v107
	v_cvt_pk_bf16_f32 v122, v108, v109
	v_cvt_pk_bf16_f32 v123, v110, v111
	global_store_dwordx4 v57, v[120:123], s[72:73]
	s_waitcnt lgkmcnt(1)
	v_cvt_pk_bf16_f32 v124, v112, v113
	v_cvt_pk_bf16_f32 v125, v114, v115
	v_cvt_pk_bf16_f32 v126, v116, v117
	v_cvt_pk_bf16_f32 v127, v118, v119
	global_store_dwordx4 v57, v[124:127], s[78:79]
	s_waitcnt lgkmcnt(0)
	v_readfirstlane_b32 s5, v82
	s_mov_b32 s3, s4
	s_mov_b32 s4, s5
	s_branch .Ldcv0_loop
.Ldcv0_last:
	s_cmp_lt_u32 s3, 0x800
	s_cbranch_scc0 .Ldcv0_dup_la
	s_lshr_b32 s6, s3, 5
	s_and_b32 s86, s3, 31
	s_lshl_b32 s6, s6, 7
	s_add_u32 s6, s6, 0xa800000
	s_mov_b32 s87, 0
	s_branch .Ldcv0_ddn_la

; DEVI unsigned pack2(float a, float b) { f32v2 v = {a, b}; return __builtin_bit_cast(unsigned, __builtin_convertvector(v, bf16v2)); }
; DEVI void lds_barrier() { asm volatile("s_waitcnt lgkmcnt(0)" ::: "memory"); __builtin_amdgcn_s_barrier(); asm volatile("" ::: "memory"); }
; DEVI void tconv_store(const TcPre& R, u16* __restrict__ Wt, int K, int N, int t, float* lds, bool perm) {
;   const int tid = threadIdx.x;
;   const int tnN = N / 128;
;   int tk = t / tnN, tn = t % tnN, k0 = tk * 64, n0 = tn * 128;
;   {
;     float* d = lds + (tid >> 5) * 129 + (tid & 31) * 4;
;     d[0] = R.a[0]; d[1] = R.a[1]; d[2] = R.a[2]; d[3] = R.a[3];
;     d[16 * 129] = R.b[0]; d[16 * 129 + 1] = R.b[1]; d[16 * 129 + 2] = R.b[2]; d[16 * 129 + 3] = R.b[3];
;     d[32 * 129] = R.c[0]; d[32 * 129 + 1] = R.c[1]; d[32 * 129 + 2] = R.c[2]; d[32 * 129 + 3] = R.c[3];
;     d[48 * 129] = R.d[0]; d[48 * 129 + 1] = R.d[1]; d[48 * 129 + 2] = R.d[2]; d[48 * 129 + 3] = R.d[3];
;   }
;   lds_barrier();
;   int n0p = !perm ? n0 : (n0 < DFF ? (n0 / 128) * 256 : ((n0 - DFF) / 128) * 256 + 128);
; #pragma unroll
;   for (int p = 0; p < 2; ++p) {
;     int item = p * 512 + tid, n = item >> 3, kg = item & 7;
;     const float* s = lds + (kg * 8) * 129 + n;
;     uint4 o;
;     o.x = pack2(s[0], s[129]); o.y = pack2(s[2 * 129], s[3 * 129]);
;     o.z = pack2(s[4 * 129], s[5 * 129]); o.w = pack2(s[6 * 129], s[7 * 129]);
;     *(uint4*)(Wt + (size_t)(n0p + n) * K + k0 + kg * 8) = o;
;   }
;   lds_barrier();
; }
.Ldcv0_ddn_la:
	s_add_u32 s84, s56, s6
	s_addc_u32 s85, s57, 0
	s_waitcnt vmcnt(0)
	s_add_u32 s6, s86, 0
	s_cmp_eq_u32 s87, 0
	s_cbranch_scc1 .Ldcv0_np_la0
	s_lshl_b32 s7, s6, 8
	s_sub_u32 s15, s7, 0x5580
	s_cmp_lt_u32 s6, 86
	s_cselect_b32 s6, s7, s15
	s_lshl_b32 s6, s6, 13
	s_branch .Ldcv0_npd_la0

; DEVI unsigned pack2(float a, float b) { f32v2 v = {a, b}; return __builtin_bit_cast(unsigned, __builtin_convertvector(v, bf16v2)); }
; DEVI void lds_barrier() { asm volatile("s_waitcnt lgkmcnt(0)" ::: "memory"); __builtin_amdgcn_s_barrier(); asm volatile("" ::: "memory"); }
; DEVI void tconv_store(const TcPre& R, u16* __restrict__ Wt, int K, int N, int t, float* lds, bool perm) {
;   const int tid = threadIdx.x;
;   const int tnN = N / 128;
;   int tk = t / tnN, tn = t % tnN, k0 = tk * 64, n0 = tn * 128;
;   {
;     float* d = lds + (tid >> 5) * 129 + (tid & 31) * 4;
;     d[0] = R.a[0]; d[1] = R.a[1]; d[2] = R.a[2]; d[3] = R.a[3];
;     d[16 * 129] = R.b[0]; d[16 * 129 + 1] = R.b[1]; d[16 * 129 + 2] = R.b[2]; d[16 * 129 + 3] = R.b[3];
;     d[32 * 129] = R.c[0]; d[32 * 129 + 1] = R.c[1]; d[32 * 129 + 2] = R.c[2]; d[32 * 129 + 3] = R.c[3];
;     d[48 * 129] = R.d[0]; d[48 * 129 + 1] = R.d[1]; d[48 * 129 + 2] = R.d[2]; d[48 * 129 + 3] = R.d[3];
;   }
;   lds_barrier();
;   int n0p = !perm ? n0 : (n0 < DFF ? (n0 / 128) * 256 : ((n0 - DFF) / 128) * 256 + 128);
; #pragma unroll
;   for (int p = 0; p < 2; ++p) {
;     int item = p * 512 + tid, n = item >> 3, kg = item & 7;
;     const float* s = lds + (kg * 8) * 129 + n;
;     uint4 o;
;     o.x = pack2(s[0], s[129]); o.y = pack2(s[2 * 129], s[3 * 129]);
;     o.z = pack2(s[4 * 129], s[5 * 129]); o.w = pack2(s[6 * 129], s[7 * 129]);
;     *(uint4*)(Wt + (size_t)(n0p + n) * K + k0 + kg * 8) = o;
;   }
;   lds_barrier();
; }
.Ldcv0_npd_la0:
	s_add_u32 s72, s84, s6
	s_addc_u32 s73, s85, 0
	s_add_u32 s78, s72, 0x80000
	s_addc_u32 s79, s73, 0
	ds_write2_b32 v58, v168, v169 offset1:1
	ds_write2_b32 v58, v170, v171 offset0:2 offset1:3
	ds_write2_b32 v59, v172, v173 offset1:1
	ds_write2_b32 v59, v174, v175 offset0:2 offset1:3
	ds_write2_b32 v60, v176, v177 offset1:1
	ds_write2_b32 v60, v178, v179 offset0:2 offset1:3
	ds_write2_b32 v61, v180, v181 offset1:1
	ds_write2_b32 v61, v182, v183 offset0:2 offset1:3
	s_waitcnt lgkmcnt(0)
	s_barrier
	ds_read2_b32 v[104:105], v66 offset1:129
	ds_read2_b32 v[106:107], v67 offset1:129
	ds_read2_b32 v[108:109], v68 offset1:129
	ds_read2_b32 v[110:111], v69 offset1:129
	ds_read2_b32 v[112:113], v70 offset1:129
	ds_read2_b32 v[114:115], v71 offset1:129
	ds_read2_b32 v[116:117], v72 offset1:129
	ds_read2_b32 v[118:119], v73 offset1:129
	s_waitcnt lgkmcnt(4)
	v_cvt_pk_bf16_f32 v120, v104, v105
	v_cvt_pk_bf16_f32 v121, v106, v107
	v_cvt_pk_bf16_f32 v122, v108, v109
	v_cvt_pk_bf16_f32 v123, v110, v111
	global_store_dwordx4 v57, v[120:123], s[72:73]
	s_waitcnt lgkmcnt(0)
	v_cvt_pk_bf16_f32 v124, v112, v113
	v_cvt_pk_bf16_f32 v125, v114, v115
	v_cvt_pk_bf16_f32 v126, v116, v117
	v_cvt_pk_bf16_f32 v127, v118, v119
	global_store_dwordx4 v57, v[124:127], s[78:79]
	s_add_u32 s6, s86, 1
	s_cmp_eq_u32 s87, 0
	s_cbranch_scc1 .Ldcv0_np_la1
	s_lshl_b32 s7, s6, 8
	s_sub_u32 s15, s7, 0x5580
	s_cmp_lt_u32 s6, 86
	s_cselect_b32 s6, s7, s15
	s_lshl_b32 s6, s6, 13
	s_branch .Ldcv0_npd_la1

; DEVI unsigned pack2(float a, float b) { f32v2 v = {a, b}; return __builtin_bit_cast(unsigned, __builtin_convertvector(v, bf16v2)); }
; DEVI void lds_barrier() { asm volatile("s_waitcnt lgkmcnt(0)" ::: "memory"); __builtin_amdgcn_s_barrier(); asm volatile("" ::: "memory"); }
; DEVI void tconv_store(const TcPre& R, u16* __restrict__ Wt, int K, int N, int t, float* lds, bool perm) {
;   const int tid = threadIdx.x;
;   const int tnN = N / 128;
;   int tk = t / tnN, tn = t % tnN, k0 = tk * 64, n0 = tn * 128;
;   {
;     float* d = lds + (tid >> 5) * 129 + (tid & 31) * 4;
;     d[0] = R.a[0]; d[1] = R.a[1]; d[2] = R.a[2]; d[3] = R.a[3];
;     d[16 * 129] = R.b[0]; d[16 * 129 + 1] = R.b[1]; d[16 * 129 + 2] = R.b[2]; d[16 * 129 + 3] = R.b[3];
;     d[32 * 129] = R.c[0]; d[32 * 129 + 1] = R.c[1]; d[32 * 129 + 2] = R.c[2]; d[32 * 129 + 3] = R.c[3];
;     d[48 * 129] = R.d[0]; d[48 * 129 + 1] = R.d[1]; d[48 * 129 + 2] = R.d[2]; d[48 * 129 + 3] = R.d[3];
;   }
;   lds_barrier();
;   int n0p = !perm ? n0 : (n0 < DFF ? (n0 / 128) * 256 : ((n0 - DFF) / 128) * 256 + 128);
; #pragma unroll
;   for (int p = 0; p < 2; ++p) {
;     int item = p * 512 + tid, n = item >> 3, kg = item & 7;
;     const float* s = lds + (kg * 8) * 129 + n;
;     uint4 o;
;     o.x = pack2(s[0], s[129]); o.y = pack2(s[2 * 129], s[3 * 129]);
;     o.z = pack2(s[4 * 129], s[5 * 129]); o.w = pack2(s[6 * 129], s[7 * 129]);
;     *(uint4*)(Wt + (size_t)(n0p + n) * K + k0 + kg * 8) = o;
;   }
;   lds_barrier();
; }
.Ldcv0_npd_la1:
	s_add_u32 s72, s84, s6
	s_addc_u32 s73, s85, 0
	s_add_u32 s78, s72, 0x80000
	s_addc_u32 s79, s73, 0
	ds_write2_b32 v62, v184, v185 offset1:1
	ds_write2_b32 v62, v186, v187 offset0:2 offset1:3
	ds_write2_b32 v63, v188, v189 offset1:1
	ds_write2_b32 v63, v190, v191 offset0:2 offset1:3
	ds_write2_b32 v64, v192, v193 offset1:1
	ds_write2_b32 v64, v194, v195 offset0:2 offset1:3
	ds_write2_b32 v65, v196, v197 offset1:1
	ds_write2_b32 v65, v198, v199 offset0:2 offset1:3
	s_waitcnt lgkmcnt(0)
	s_barrier
	ds_read2_b32 v[104:105], v74 offset1:129
	ds_read2_b32 v[106:107], v75 offset1:129
	ds_read2_b32 v[108:109], v76 offset1:129
	ds_read2_b32 v[110:111], v77 offset1:129
	ds_read2_b32 v[112:113], v78 offset1:129
	ds_read2_b32 v[114:115], v79 offset1:129
	ds_read2_b32 v[116:117], v80 offset1:129
	ds_read2_b32 v[118:119], v81 offset1:129
	s_waitcnt lgkmcnt(4)
	v_cvt_pk_bf16_f32 v120, v104, v105
	v_cvt_pk_bf16_f32 v121, v106, v107
	v_cvt_pk_bf16_f32 v122, v108, v109
	v_cvt_pk_bf16_f32 v123, v110, v111
	global_store_dwordx4 v57, v[120:123], s[72:73]
	s_waitcnt lgkmcnt(0)
	v_cvt_pk_bf16_f32 v124, v112, v113
	v_cvt_pk_bf16_f32 v125, v114, v115
	v_cvt_pk_bf16_f32 v126, v116, v117
	v_cvt_pk_bf16_f32 v127, v118, v119
	global_store_dwordx4 v57, v[124:127], s[78:79]
	s_add_u32 s6, s86, 2
	s_cmp_eq_u32 s87, 0
	s_cbranch_scc1 .Ldcv0_np_la2
	s_lshl_b32 s7, s6, 8
	s_sub_u32 s15, s7, 0x5580
	s_cmp_lt_u32 s6, 86
	s_cselect_b32 s6, s7, s15
	s_lshl_b32 s6, s6, 13
	s_branch .Ldcv0_npd_la2

; DEVI unsigned pack2(float a, float b) { f32v2 v = {a, b}; return __builtin_bit_cast(unsigned, __builtin_convertvector(v, bf16v2)); }
; DEVI void lds_barrier() { asm volatile("s_waitcnt lgkmcnt(0)" ::: "memory"); __builtin_amdgcn_s_barrier(); asm volatile("" ::: "memory"); }
; DEVI void tconv_store(const TcPre& R, u16* __restrict__ Wt, int K, int N, int t, float* lds, bool perm) {
;   const int tid = threadIdx.x;
;   const int tnN = N / 128;
;   int tk = t / tnN, tn = t % tnN, k0 = tk * 64, n0 = tn * 128;
;   {
;     float* d = lds + (tid >> 5) * 129 + (tid & 31) * 4;
;     d[0] = R.a[0]; d[1] = R.a[1]; d[2] = R.a[2]; d[3] = R.a[3];
;     d[16 * 129] = R.b[0]; d[16 * 129 + 1] = R.b[1]; d[16 * 129 + 2] = R.b[2]; d[16 * 129 + 3] = R.b[3];
;     d[32 * 129] = R.c[0]; d[32 * 129 + 1] = R.c[1]; d[32 * 129 + 2] = R.c[2]; d[32 * 129 + 3] = R.c[3];
;     d[48 * 129] = R.d[0]; d[48 * 129 + 1] = R.d[1]; d[48 * 129 + 2] = R.d[2]; d[48 * 129 + 3] = R.d[3];
;   }
;   lds_barrier();
;   int n0p = !perm ? n0 : (n0 < DFF ? (n0 / 128) * 256 : ((n0 - DFF) / 128) * 256 + 128);
; #pragma unroll
;   for (int p = 0; p < 2; ++p) {
;     int item = p * 512 + tid, n = item >> 3, kg = item & 7;
;     const float* s = lds + (kg * 8) * 129 + n;
;     uint4 o;
;     o.x = pack2(s[0], s[129]); o.y = pack2(s[2 * 129], s[3 * 129]);
;     o.z = pack2(s[4 * 129], s[5 * 129]); o.w = pack2(s[6 * 129], s[7 * 129]);
;     *(uint4*)(Wt + (size_t)(n0p + n) * K + k0 + kg * 8) = o;
;   }
;   lds_barrier();
; }
.Ldcv0_npd_la2:
	s_add_u32 s72, s84, s6
	s_addc_u32 s73, s85, 0
	s_add_u32 s78, s72, 0x80000
	s_addc_u32 s79, s73, 0
	ds_write2_b32 v58, v200, v201 offset1:1
	ds_write2_b32 v58, v202, v203 offset0:2 offset1:3
	ds_write2_b32 v59, v204, v205 offset1:1
	ds_write2_b32 v59, v206, v207 offset0:2 offset1:3
	ds_write2_b32 v60, v208, v209 offset1:1
	ds_write2_b32 v60, v210, v211 offset0:2 offset1:3
	ds_write2_b32 v61, v212, v213 offset1:1
	ds_write2_b32 v61, v214, v215 offset0:2 offset1:3
	s_waitcnt lgkmcnt(0)
	s_barrier
	ds_read2_b32 v[104:105], v66 offset1:129
	ds_read2_b32 v[106:107], v67 offset1:129
	ds_read2_b32 v[108:109], v68 offset1:129
	ds_read2_b32 v[110:111], v69 offset1:129
	ds_read2_b32 v[112:113], v70 offset1:129
	ds_read2_b32 v[114:115], v71 offset1:129
	ds_read2_b32 v[116:117], v72 offset1:129
	ds_read2_b32 v[118:119], v73 offset1:129
	s_waitcnt lgkmcnt(4)
	v_cvt_pk_bf16_f32 v120, v104, v105
	v_cvt_pk_bf16_f32 v121, v106, v107
	v_cvt_pk_bf16_f32 v122, v108, v109
	v_cvt_pk_bf16_f32 v123, v110, v111
	global_store_dwordx4 v57, v[120:123], s[72:73]
	s_waitcnt lgkmcnt(0)
	v_cvt_pk_bf16_f32 v124, v112, v113
	v_cvt_pk_bf16_f32 v125, v114, v115
	v_cvt_pk_bf16_f32 v126, v116, v117
	v_cvt_pk_bf16_f32 v127, v118, v119
	global_store_dwordx4 v57, v[124:127], s[78:79]
	s_add_u32 s6, s86, 3
	s_cmp_eq_u32 s87, 0
	s_cbranch_scc1 .Ldcv0_np_la3
	s_lshl_b32 s7, s6, 8
	s_sub_u32 s15, s7, 0x5580
	s_cmp_lt_u32 s6, 86
	s_cselect_b32 s6, s7, s15
	s_lshl_b32 s6, s6, 13
	s_branch .Ldcv0_npd_la3

; DEVI unsigned pack2(float a, float b) { f32v2 v = {a, b}; return __builtin_bit_cast(unsigned, __builtin_convertvector(v, bf16v2)); }
; DEVI void lds_barrier() { asm volatile("s_waitcnt lgkmcnt(0)" ::: "memory"); __builtin_amdgcn_s_barrier(); asm volatile("" ::: "memory"); }
; DEVI void tconv_store(const TcPre& R, u16* __restrict__ Wt, int K, int N, int t, float* lds, bool perm) {
;   const int tid = threadIdx.x;
;   const int tnN = N / 128;
;   int tk = t / tnN, tn = t % tnN, k0 = tk * 64, n0 = tn * 128;
;   {
;     float* d = lds + (tid >> 5) * 129 + (tid & 31) * 4;
;     d[0] = R.a[0]; d[1] = R.a[1]; d[2] = R.a[2]; d[3] = R.a[3];
;     d[16 * 129] = R.b[0]; d[16 * 129 + 1] = R.b[1]; d[16 * 129 + 2] = R.b[2]; d[16 * 129 + 3] = R.b[3];
;     d[32 * 129] = R.c[0]; d[32 * 129 + 1] = R.c[1]; d[32 * 129 + 2] = R.c[2]; d[32 * 129 + 3] = R.c[3];
;     d[48 * 129] = R.d[0]; d[48 * 129 + 1] = R.d[1]; d[48 * 129 + 2] = R.d[2]; d[48 * 129 + 3] = R.d[3];
;   }
;   lds_barrier();
;   int n0p = !perm ? n0 : (n0 < DFF ? (n0 / 128) * 256 : ((n0 - DFF) / 128) * 256 + 128);
; #pragma unroll
;   for (int p = 0; p < 2; ++p) {
;     int item = p * 512 + tid, n = item >> 3, kg = item & 7;
;     const float* s = lds + (kg * 8) * 129 + n;
;     uint4 o;
;     o.x = pack2(s[0], s[129]); o.y = pack2(s[2 * 129], s[3 * 129]);
;     o.z = pack2(s[4 * 129], s[5 * 129]); o.w = pack2(s[6 * 129], s[7 * 129]);
;     *(uint4*)(Wt + (size_t)(n0p + n) * K + k0 + kg * 8) = o;
;   }
;   lds_barrier();
; }
; __device__ __forceinline__ void xcd_barrier(const XcdBarrier& b) {
;     asm volatile("s_waitcnt vmcnt(0)" ::: "memory");
;     __syncthreads();
;     if (threadIdx.x == 0) {
;         unsigned* bar = b.bar;
;         __builtin_amdgcn_s_waitcnt(0);
;         const unsigned old = xb_add(&bar[XB_XSUB(b.x)], 1u);
;         const unsigned gen = old / b.nloc;
;         if (old + 1u == (gen + 1u) * b.nloc) {
;             __builtin_amdgcn_fence(__ATOMIC_RELEASE, "agent");
;             asm volatile("s_waitcnt vmcnt(0)" ::: "memory");
;             const unsigned og = xb_add(&bar[XB_TOP], 1u);
;             const unsigned tg = og / b.nx;
;             if (og + 1u == (tg + 1u) * b.nx) xb_add(&bar[XB_TOPGEN], 1u);
;             else XB_SPIN(xb_ld(&bar[XB_TOPGEN]) == tg, bar);
;             __builtin_amdgcn_fence(__ATOMIC_ACQUIRE, "agent");
;             xb_add(&bar[XB_XGEN(b.x)], 1u);
.Ldcv0_npd_la3:
	s_add_u32 s72, s84, s6
	s_addc_u32 s73, s85, 0
	s_add_u32 s78, s72, 0x80000
	s_addc_u32 s79, s73, 0
	ds_write2_b32 v62, v216, v217 offset1:1
	ds_write2_b32 v62, v218, v219 offset0:2 offset1:3
	ds_write2_b32 v63, v220, v221 offset1:1
	ds_write2_b32 v63, v222, v223 offset0:2 offset1:3
	ds_write2_b32 v64, v224, v225 offset1:1
	ds_write2_b32 v64, v226, v227 offset0:2 offset1:3
	ds_write2_b32 v65, v228, v229 offset1:1
	ds_write2_b32 v65, v230, v231 offset0:2 offset1:3
	s_waitcnt lgkmcnt(0)
	s_barrier
	ds_read2_b32 v[104:105], v74 offset1:129
	ds_read2_b32 v[106:107], v75 offset1:129
	ds_read2_b32 v[108:109], v76 offset1:129
	ds_read2_b32 v[110:111], v77 offset1:129
	ds_read2_b32 v[112:113], v78 offset1:129
	ds_read2_b32 v[114:115], v79 offset1:129
	ds_read2_b32 v[116:117], v80 offset1:129
	ds_read2_b32 v[118:119], v81 offset1:129
	s_waitcnt lgkmcnt(4)
	v_cvt_pk_bf16_f32 v120, v104, v105
	v_cvt_pk_bf16_f32 v121, v106, v107
	v_cvt_pk_bf16_f32 v122, v108, v109
	v_cvt_pk_bf16_f32 v123, v110, v111
	global_store_dwordx4 v57, v[120:123], s[72:73]
	s_waitcnt lgkmcnt(0)
	v_cvt_pk_bf16_f32 v124, v112, v113
	v_cvt_pk_bf16_f32 v125, v114, v115
	v_cvt_pk_bf16_f32 v126, v116, v117
	v_cvt_pk_bf16_f32 v127, v118, v119
	global_store_dwordx4 v57, v[124:127], s[78:79]
.Ldcv0_done:
	s_waitcnt lgkmcnt(0)
	s_barrier
.LBB0_236:
	s_cmp_lt_i32 s58, 3
	s_cselect_b64 s[38:39], -1, 0
	s_cmp_gt_i32 s58, 2
	s_cselect_b64 s[4:5], -1, 0
	s_cmp_lt_i32 s59, 3
	s_cselect_b64 s[6:7], -1, 0
	s_or_b64 s[4:5], s[4:5], s[6:7]
	s_and_b64 vcc, exec, s[4:5]
	s_cbranch_vccnz .LBB0_328
	s_andn2_b64 vcc, exec, s[8:9]
	s_cbranch_vccnz .LBB0_276
	s_waitcnt vmcnt(0)
	s_waitcnt vmcnt(0)
	s_barrier
	s_and_saveexec_b64 s[4:5], s[0:1]
	s_cbranch_execz .LBB0_275
	s_mov_b64 s[6:7], exec
	v_mbcnt_lo_u32_b32 v0, s6, 0
	v_readlane_b32 s3, v255, 0
	v_mbcnt_hi_u32_b32 v0, s7, v0
	s_lshl_b32 s3, s3, 6
	s_mov_b32 s11, 0
	v_cmp_eq_u32_e32 vcc, 0, v0
	s_waitcnt vmcnt(0) expcnt(0) lgkmcnt(0)
	s_and_saveexec_b64 s[8:9], vcc
	s_cbranch_execz .LBB0_241
	s_add_i32 s10, s3, 0x500
	s_lshl_b64 s[10:11], s[10:11], 2
	s_add_u32 s10, s94, s10
	s_addc_u32 s11, s95, s11
	s_bcnt1_i32_b64 s6, s[6:7]
	v_mov_b32_e32 v1, 0
	v_mov_b32_e32 v2, s6
	global_atomic_add v1, v1, v2, s[10:11] sc0

; DEVI void lds_barrier() { asm volatile("s_waitcnt lgkmcnt(0)" ::: "memory"); __builtin_amdgcn_s_barrier(); asm volatile("" ::: "memory"); }
; DEVI void deferred_conv(const Params& p, char* smem, const int which) {
;   float* lds = (float*)smem;
;   int* qs = (int*)(smem + 40960);
;   unsigned* ctr = (unsigned*)(p.ws + O_CTR) + which * 16;
;   const int tlo = which ? DQ_WO + DQ_WUP : 0, thi = which ? DQ_TOTAL : DQ_WO + DQ_WUP;
;   char* ws = p.ws;
;   for (;;) {
;     if (threadIdx.x == 0) *qs = tlo + (int)atomicAdd(ctr, (unsigned)DQ_GRAB);
;     lds_barrier();
;     int base = *qs;
;     lds_barrier();
;     if (base >= thi) break;
;     TcPre R[DQ_GRAB];
; #pragma unroll
;     for (int u = 0; u < DQ_GRAB; ++u) {
;       int t = base + u;
;       if (t < thi) {
;         if (t < DQ_WO) tconv_load(p.w_o, 4096, t, R[u]);
;         else if (t < DQ_WO + DQ_WUP) tconv_load(p.w_up, NUP, t - DQ_WO, R[u]);
;         else tconv_load(p.w_down, 4096, t - DQ_WO - DQ_WUP, R[u]);
;       }
;     }
.LBB0_666:
	s_waitcnt lgkmcnt(0)
	s_barrier
	v_mov_b32_e32 v50, 0
	v_mov_b32_e32 v51, 4
	v_mov_b32_e32 v84, 0x10400
	v_lshrrev_b32_e32 v55, 5, v164
	v_and_b32_e32 v56, 31, v164
	v_lshlrev_b32_e32 v56, 4, v56
	v_lshrrev_b32_e32 v53, 3, v164
	v_and_b32_e32 v57, 7, v164
	v_lshlrev_b32_e32 v57, 4, v57
	s_mov_b32 s6, 0x5600
	v_mad_u32_u24 v57, v53, s6, v57
	s_movk_i32 s6, 0x204
	v_mad_u32_u24 v58, v55, s6, v56
	v_add_u32_e32 v59, 0x2040, v58
	v_add_u32_e32 v60, 0x4080, v58
	v_add_u32_e32 v61, 0x60c0, v58
	v_add_u32_e32 v62, 0x8100, v58
	v_add_u32_e32 v63, 0xa140, v58
	v_add_u32_e32 v64, 0xc180, v58
	v_add_u32_e32 v65, 0xe1c0, v58
	v_and_b32_e32 v66, 7, v164
	s_movk_i32 s6, 0x1020
	v_lshlrev_b32_e32 v53, 2, v53
	v_mad_u32_u24 v66, v66, s6, v53
	v_add_u32_e32 v67, 0x408, v66
	v_add_u32_e32 v68, 0x810, v66
	v_add_u32_e32 v69, 0xc18, v66
	v_add_u32_e32 v70, 0x100, v66
	v_add_u32_e32 v71, 0x508, v66
	v_add_u32_e32 v72, 0x910, v66
	v_add_u32_e32 v73, 0xd18, v66
	v_add_u32_e32 v74, 0x8100, v66
	v_add_u32_e32 v75, 0x8508, v66
	v_add_u32_e32 v76, 0x8910, v66
	v_add_u32_e32 v77, 0x8d18, v66
	v_add_u32_e32 v78, 0x8200, v66
	v_add_u32_e32 v79, 0x8608, v66
	v_add_u32_e32 v80, 0x8a10, v66
	v_add_u32_e32 v81, 0x8e18, v66
	s_add_u32 s10, s56, 0x2b403040
	s_addc_u32 s11, s57, 0
	v_readfirstlane_b32 s33, v164
	s_mov_b64 s[76:77], exec
	s_cmp_lg_u32 s33, 0
	s_cbranch_scc1 .Ldcv1_q0
	s_mov_b64 exec, 1
	global_atomic_add v82, v50, v51, s[10:11] sc0
	global_atomic_add v83, v50, v51, s[10:11] sc0
	s_waitcnt vmcnt(0)
	ds_write_b64 v84, v[82:83]
	s_mov_b64 exec, s[76:77]
.Ldcv1_q0:
	s_waitcnt lgkmcnt(0)
	s_barrier
	ds_read_b64 v[82:83], v84
	s_waitcnt lgkmcnt(0)
	v_readfirstlane_b32 s3, v82
	v_readfirstlane_b32 s4, v83
	s_cmp_ge_u32 s3, 0x1580
	s_cbranch_scc1 .Ldcv1_done
	s_lshr_b32 s6, s3, 5
	s_and_b32 s7, s3, 31
	s_lshl_b32 s6, s6, 20
	s_lshl_b32 s7, s7, 9
	s_add_u32 s6, s6, s7
	s_add_u32 s68, s28, s6
	s_addc_u32 s69, s29, 0
	s_mov_b32 s70, 0x40000
	s_movk_i32 s88, 0x4000
	v_mad_u32_u24 v54, v55, s88, v56
	global_load_dwordx4 v[168:171], v54, s[68:69]
	s_add_u32 s68, s68, s70
	s_addc_u32 s69, s69, 0
	global_load_dwordx4 v[172:175], v54, s[68:69]
	s_add_u32 s68, s68, s70
	s_addc_u32 s69, s69, 0
	global_load_dwordx4 v[176:179], v54, s[68:69]
	s_add_u32 s68, s68, s70
	s_addc_u32 s69, s69, 0
	global_load_dwordx4 v[180:183], v54, s[68:69]
	s_mul_i32 s6, s70, 3
	s_sub_u32 s68, s68, s6
	s_subb_u32 s69, s69, 0
	s_add_u32 s68, s68, 0x200
	s_addc_u32 s69, s69, 0
	global_load_dwordx4 v[184:187], v54, s[68:69]
	s_add_u32 s68, s68, s70
	s_addc_u32 s69, s69, 0
	global_load_dwordx4 v[188:191], v54, s[68:69]
	s_add_u32 s68, s68, s70
	s_addc_u32 s69, s69, 0
	global_load_dwordx4 v[192:195], v54, s[68:69]
	s_add_u32 s68, s68, s70
	s_addc_u32 s69, s69, 0
	global_load_dwordx4 v[196:199], v54, s[68:69]
	s_mul_i32 s6, s70, 3
	s_sub_u32 s68, s68, s6
	s_subb_u32 s69, s69, 0
	s_add_u32 s68, s68, 0x200
	s_addc_u32 s69, s69, 0
	global_load_dwordx4 v[200:203], v54, s[68:69]
	s_add_u32 s68, s68, s70
	s_addc_u32 s69, s69, 0
	global_load_dwordx4 v[204:207], v54, s[68:69]
	s_add_u32 s68, s68, s70
	s_addc_u32 s69, s69, 0
	global_load_dwordx4 v[208:211], v54, s[68:69]
	s_add_u32 s68, s68, s70
	s_addc_u32 s69, s69, 0
	global_load_dwordx4 v[212:215], v54, s[68:69]
	s_mul_i32 s6, s70, 3
	s_sub_u32 s68, s68, s6
	s_subb_u32 s69, s69, 0
	s_add_u32 s68, s68, 0x200
	s_addc_u32 s69, s69, 0
	global_load_dwordx4 v[216:219], v54, s[68:69]
	s_add_u32 s68, s68, s70
	s_addc_u32 s69, s69, 0
	global_load_dwordx4 v[220:223], v54, s[68:69]
	s_add_u32 s68, s68, s70
	s_addc_u32 s69, s69, 0
	global_load_dwordx4 v[224:227], v54, s[68:69]
	s_add_u32 s68, s68, s70
	s_addc_u32 s69, s69, 0
	global_load_dwordx4 v[228:231], v54, s[68:69]
	s_mul_i32 s6, s70, 3
	s_sub_u32 s68, s68, s6
	s_subb_u32 s69, s69, 0
	s_add_u32 s68, s68, 0x200
	s_addc_u32 s69, s69, 0
	s_waitcnt vmcnt(0)
.Ldcv1_loop:
	s_cmp_ge_u32 s4, 0x1580
	s_cbranch_scc1 .Ldcv1_last
	s_lshr_b32 s6, s3, 5
	s_and_b32 s86, s3, 31
	s_lshl_b32 s6, s6, 7
	s_add_u32 s6, s6, 0x17400000
	s_add_u32 s84, s56, s6
	s_addc_u32 s85, s57, 0
	s_lshr_b32 s6, s4, 5
	s_and_b32 s7, s4, 31
	s_lshl_b32 s6, s6, 20
	s_lshl_b32 s7, s7, 9
	s_add_u32 s6, s6, s7
	s_add_u32 s68, s28, s6
	s_addc_u32 s69, s29, 0
	s_mov_b32 s70, 0x40000
	s_movk_i32 s88, 0x4000
	v_mad_u32_u24 v54, v55, s88, v56
	s_cmp_lg_u32 s33, 0
	s_cbranch_scc1 .Ldcv1_a_st
	s_mov_b64 exec, 1
	global_atomic_add v52, v50, v51, s[10:11] sc0
	s_mov_b64 exec, s[76:77]
; DEVI unsigned pack2(float a, float b) { f32v2 v = {a, b}; return __builtin_bit_cast(unsigned, __builtin_convertvector(v, bf16v2)); }
; DEVI void lds_barrier() { asm volatile("s_waitcnt lgkmcnt(0)" ::: "memory"); __builtin_amdgcn_s_barrier(); asm volatile("" ::: "memory"); }
; DEVI void tconv_store(const TcPre& R, u16* __restrict__ Wt, int K, int N, int t, float* lds, bool perm) {
;   const int tid = threadIdx.x;
;   const int tnN = N / 128;
;   int tk = t / tnN, tn = t % tnN, k0 = tk * 64, n0 = tn * 128;
;   {
;     float* d = lds + (tid >> 5) * 129 + (tid & 31) * 4;
;     d[0] = R.a[0]; d[1] = R.a[1]; d[2] = R.a[2]; d[3] = R.a[3];
;     d[16 * 129] = R.b[0]; d[16 * 129 + 1] = R.b[1]; d[16 * 129 + 2] = R.b[2]; d[16 * 129 + 3] = R.b[3];
;     d[32 * 129] = R.c[0]; d[32 * 129 + 1] = R.c[1]; d[32 * 129 + 2] = R.c[2]; d[32 * 129 + 3] = R.c[3];
;     d[48 * 129] = R.d[0]; d[48 * 129 + 1] = R.d[1]; d[48 * 129 + 2] = R.d[2]; d[48 * 129 + 3] = R.d[3];
;   }
;   lds_barrier();
;   int n0p = !perm ? n0 : (n0 < DFF ? (n0 / 128) * 256 : ((n0 - DFF) / 128) * 256 + 128);
; #pragma unroll
;   for (int p = 0; p < 2; ++p) {
;     int item = p * 512 + tid, n = item >> 3, kg = item & 7;
;     const float* s = lds + (kg * 8) * 129 + n;
;     uint4 o;
;     o.x = pack2(s[0], s[129]); o.y = pack2(s[2 * 129], s[3 * 129]);
;     o.z = pack2(s[4 * 129], s[5 * 129]); o.w = pack2(s[6 * 129], s[7 * 129]);
;     *(uint4*)(Wt + (size_t)(n0p + n) * K + k0 + kg * 8) = o;
;   }
;   lds_barrier();
; }
.Ldcv1_a_st:
	s_add_u32 s6, s86, 0
	s_mul_i32 s6, s6, 0x2b0000
	s_add_u32 s72, s84, s6
	s_addc_u32 s73, s85, 0
	s_add_u32 s78, s72, 0x158000
	s_addc_u32 s79, s73, 0
	s_waitcnt vmcnt(20)
	ds_write2_b32 v58, v168, v169 offset1:1
	ds_write2_b32 v58, v170, v171 offset0:2 offset1:3
	ds_write2_b32 v59, v172, v173 offset1:1
	ds_write2_b32 v59, v174, v175 offset0:2 offset1:3
	ds_write2_b32 v60, v176, v177 offset1:1
	ds_write2_b32 v60, v178, v179 offset0:2 offset1:3
	ds_write2_b32 v61, v180, v181 offset1:1
	ds_write2_b32 v61, v182, v183 offset0:2 offset1:3
	global_load_dwordx4 v[168:171], v54, s[68:69]
	s_add_u32 s68, s68, s70
	s_addc_u32 s69, s69, 0
	global_load_dwordx4 v[172:175], v54, s[68:69]
	s_add_u32 s68, s68, s70
	s_addc_u32 s69, s69, 0
	global_load_dwordx4 v[176:179], v54, s[68:69]
	s_add_u32 s68, s68, s70
	s_addc_u32 s69, s69, 0
	global_load_dwordx4 v[180:183], v54, s[68:69]
	s_mul_i32 s6, s70, 3
	s_sub_u32 s68, s68, s6
	s_subb_u32 s69, s69, 0
	s_add_u32 s68, s68, 0x200
	s_addc_u32 s69, s69, 0
	s_waitcnt lgkmcnt(0)
	s_barrier
	ds_read2_b32 v[104:105], v66 offset1:129
	ds_read2_b32 v[106:107], v67 offset1:129
	ds_read2_b32 v[108:109], v68 offset1:129
	ds_read2_b32 v[110:111], v69 offset1:129
	ds_read2_b32 v[112:113], v70 offset1:129
	ds_read2_b32 v[114:115], v71 offset1:129
	ds_read2_b32 v[116:117], v72 offset1:129
	ds_read2_b32 v[118:119], v73 offset1:129
	s_waitcnt lgkmcnt(4)
	v_cvt_pk_bf16_f32 v120, v104, v105
	v_cvt_pk_bf16_f32 v121, v106, v107
	v_cvt_pk_bf16_f32 v122, v108, v109
	v_cvt_pk_bf16_f32 v123, v110, v111
	global_store_dwordx4 v57, v[120:123], s[72:73]
	s_waitcnt lgkmcnt(0)
	v_cvt_pk_bf16_f32 v124, v112, v113
	v_cvt_pk_bf16_f32 v125, v114, v115
	v_cvt_pk_bf16_f32 v126, v116, v117
	v_cvt_pk_bf16_f32 v127, v118, v119
	global_store_dwordx4 v57, v[124:127], s[78:79]
	s_add_u32 s6, s86, 1
	s_mul_i32 s6, s6, 0x2b0000
	s_add_u32 s72, s84, s6
	s_addc_u32 s73, s85, 0
	s_add_u32 s78, s72, 0x158000
	s_addc_u32 s79, s73, 0
	s_waitcnt vmcnt(20)
	ds_write2_b32 v62, v184, v185 offset1:1
	ds_write2_b32 v62, v186, v187 offset0:2 offset1:3
	ds_write2_b32 v63, v188, v189 offset1:1
	ds_write2_b32 v63, v190, v191 offset0:2 offset1:3
	ds_write2_b32 v64, v192, v193 offset1:1
	ds_write2_b32 v64, v194, v195 offset0:2 offset1:3
	ds_write2_b32 v65, v196, v197 offset1:1
	ds_write2_b32 v65, v198, v199 offset0:2 offset1:3
	global_load_dwordx4 v[184:187], v54, s[68:69]
	s_add_u32 s68, s68, s70
	s_addc_u32 s69, s69, 0
	global_load_dwordx4 v[188:191], v54, s[68:69]
	s_add_u32 s68, s68, s70
	s_addc_u32 s69, s69, 0
	global_load_dwordx4 v[192:195], v54, s[68:69]
	s_add_u32 s68, s68, s70
	s_addc_u32 s69, s69, 0
	global_load_dwordx4 v[196:199], v54, s[68:69]
	s_mul_i32 s6, s70, 3
	s_sub_u32 s68, s68, s6
	s_subb_u32 s69, s69, 0
	s_add_u32 s68, s68, 0x200
	s_addc_u32 s69, s69, 0
	s_waitcnt lgkmcnt(0)
	s_barrier
	ds_read2_b32 v[104:105], v74 offset1:129
	ds_read2_b32 v[106:107], v75 offset1:129
	ds_read2_b32 v[108:109], v76 offset1:129
	ds_read2_b32 v[110:111], v77 offset1:129
	ds_read2_b32 v[112:113], v78 offset1:129
	ds_read2_b32 v[114:115], v79 offset1:129
	ds_read2_b32 v[116:117], v80 offset1:129
	ds_read2_b32 v[118:119], v81 offset1:129
	s_waitcnt lgkmcnt(4)
	v_cvt_pk_bf16_f32 v120, v104, v105
	v_cvt_pk_bf16_f32 v121, v106, v107
	v_cvt_pk_bf16_f32 v122, v108, v109
	v_cvt_pk_bf16_f32 v123, v110, v111
	global_store_dwordx4 v57, v[120:123], s[72:73]
	s_waitcnt lgkmcnt(0)
	v_cvt_pk_bf16_f32 v124, v112, v113
	v_cvt_pk_bf16_f32 v125, v114, v115
	v_cvt_pk_bf16_f32 v126, v116, v117
	v_cvt_pk_bf16_f32 v127, v118, v119
	global_store_dwordx4 v57, v[124:127], s[78:79]
	s_add_u32 s6, s86, 2
	s_mul_i32 s6, s6, 0x2b0000
	s_add_u32 s72, s84, s6
	s_addc_u32 s73, s85, 0
	s_add_u32 s78, s72, 0x158000
	s_addc_u32 s79, s73, 0
	s_waitcnt vmcnt(20)
	ds_write2_b32 v58, v200, v201 offset1:1
	ds_write2_b32 v58, v202, v203 offset0:2 offset1:3
	ds_write2_b32 v59, v204, v205 offset1:1
	ds_write2_b32 v59, v206, v207 offset0:2 offset1:3
	ds_write2_b32 v60, v208, v209 offset1:1
	ds_write2_b32 v60, v210, v211 offset0:2 offset1:3
	ds_write2_b32 v61, v212, v213 offset1:1
	ds_write2_b32 v61, v214, v215 offset0:2 offset1:3
	global_load_dwordx4 v[200:203], v54, s[68:69]
	s_add_u32 s68, s68, s70
	s_addc_u32 s69, s69, 0
	global_load_dwordx4 v[204:207], v54, s[68:69]
	s_add_u32 s68, s68, s70
	s_addc_u32 s69, s69, 0
	global_load_dwordx4 v[208:211], v54, s[68:69]
	s_add_u32 s68, s68, s70
	s_addc_u32 s69, s69, 0
	global_load_dwordx4 v[212:215], v54, s[68:69]
	s_mul_i32 s6, s70, 3
	s_sub_u32 s68, s68, s6
	s_subb_u32 s69, s69, 0
	s_add_u32 s68, s68, 0x200
	s_addc_u32 s69, s69, 0
	s_waitcnt lgkmcnt(0)
	s_barrier
	ds_read2_b32 v[104:105], v66 offset1:129
	ds_read2_b32 v[106:107], v67 offset1:129
	ds_read2_b32 v[108:109], v68 offset1:129
	ds_read2_b32 v[110:111], v69 offset1:129
	ds_read2_b32 v[112:113], v70 offset1:129
	ds_read2_b32 v[114:115], v71 offset1:129
	ds_read2_b32 v[116:117], v72 offset1:129
	ds_read2_b32 v[118:119], v73 offset1:129
	s_waitcnt lgkmcnt(4)
	v_cvt_pk_bf16_f32 v120, v104, v105
	v_cvt_pk_bf16_f32 v121, v106, v107
	v_cvt_pk_bf16_f32 v122, v108, v109
	v_cvt_pk_bf16_f32 v123, v110, v111
	global_store_dwordx4 v57, v[120:123], s[72:73]
	s_waitcnt lgkmcnt(0)
	v_cvt_pk_bf16_f32 v124, v112, v113
	v_cvt_pk_bf16_f32 v125, v114, v115
	v_cvt_pk_bf16_f32 v126, v116, v117
	v_cvt_pk_bf16_f32 v127, v118, v119
	global_store_dwordx4 v57, v[124:127], s[78:79]
	s_add_u32 s6, s86, 3
	s_mul_i32 s6, s6, 0x2b0000
	s_add_u32 s72, s84, s6
	s_addc_u32 s73, s85, 0
	s_add_u32 s78, s72, 0x158000
	s_addc_u32 s79, s73, 0
	s_waitcnt vmcnt(20)
	ds_write2_b32 v62, v216, v217 offset1:1
	ds_write2_b32 v62, v218, v219 offset0:2 offset1:3
	ds_write2_b32 v63, v220, v221 offset1:1
	ds_write2_b32 v63, v222, v223 offset0:2 offset1:3
	ds_write2_b32 v64, v224, v225 offset1:1
	ds_write2_b32 v64, v226, v227 offset0:2 offset1:3
	ds_write2_b32 v65, v228, v229 offset1:1
	ds_write2_b32 v65, v230, v231 offset0:2 offset1:3
	global_load_dwordx4 v[216:219], v54, s[68:69]
	s_add_u32 s68, s68, s70
	s_addc_u32 s69, s69, 0
	global_load_dwordx4 v[220:223], v54, s[68:69]
	s_add_u32 s68, s68, s70
	s_addc_u32 s69, s69, 0
	global_load_dwordx4 v[224:227], v54, s[68:69]
	s_add_u32 s68, s68, s70
	s_addc_u32 s69, s69, 0
	global_load_dwordx4 v[228:231], v54, s[68:69]
	s_mul_i32 s6, s70, 3
	s_sub_u32 s68, s68, s6
	s_subb_u32 s69, s69, 0
	s_add_u32 s68, s68, 0x200
	s_addc_u32 s69, s69, 0
	s_cmp_lg_u32 s33, 0
	s_cbranch_scc1 .Ldcv1_b_st
	s_mov_b64 exec, 1
	s_waitcnt vmcnt(22)
	ds_write_b32 v84, v52
	s_mov_b64 exec, s[76:77]

; DEVI unsigned pack2(float a, float b) { f32v2 v = {a, b}; return __builtin_bit_cast(unsigned, __builtin_convertvector(v, bf16v2)); }
; DEVI void lds_barrier() { asm volatile("s_waitcnt lgkmcnt(0)" ::: "memory"); __builtin_amdgcn_s_barrier(); asm volatile("" ::: "memory"); }
; DEVI void tconv_store(const TcPre& R, u16* __restrict__ Wt, int K, int N, int t, float* lds, bool perm) {
;   const int tid = threadIdx.x;
;   const int tnN = N / 128;
;   int tk = t / tnN, tn = t % tnN, k0 = tk * 64, n0 = tn * 128;
;   {
;     float* d = lds + (tid >> 5) * 129 + (tid & 31) * 4;
;     d[0] = R.a[0]; d[1] = R.a[1]; d[2] = R.a[2]; d[3] = R.a[3];
;     d[16 * 129] = R.b[0]; d[16 * 129 + 1] = R.b[1]; d[16 * 129 + 2] = R.b[2]; d[16 * 129 + 3] = R.b[3];
;     d[32 * 129] = R.c[0]; d[32 * 129 + 1] = R.c[1]; d[32 * 129 + 2] = R.c[2]; d[32 * 129 + 3] = R.c[3];
;     d[48 * 129] = R.d[0]; d[48 * 129 + 1] = R.d[1]; d[48 * 129 + 2] = R.d[2]; d[48 * 129 + 3] = R.d[3];
;   }
;   lds_barrier();
;   int n0p = !perm ? n0 : (n0 < DFF ? (n0 / 128) * 256 : ((n0 - DFF) / 128) * 256 + 128);
; #pragma unroll
;   for (int p = 0; p < 2; ++p) {
;     int item = p * 512 + tid, n = item >> 3, kg = item & 7;
;     const float* s = lds + (kg * 8) * 129 + n;
;     uint4 o;
;     o.x = pack2(s[0], s[129]); o.y = pack2(s[2 * 129], s[3 * 129]);
;     o.z = pack2(s[4 * 129], s[5 * 129]); o.w = pack2(s[6 * 129], s[7 * 129]);
;     *(uint4*)(Wt + (size_t)(n0p + n) * K + k0 + kg * 8) = o;
;   }
;   lds_barrier();
; }
; __device__ __forceinline__ void xcd_barrier(const XcdBarrier& b) {
;     asm volatile("s_waitcnt vmcnt(0)" ::: "memory");
;     __syncthreads();
;     if (threadIdx.x == 0) {
;         unsigned* bar = b.bar;
;         __builtin_amdgcn_s_waitcnt(0);
;         const unsigned old = xb_add(&bar[XB_XSUB(b.x)], 1u);
;         const unsigned gen = old / b.nloc;
;         if (old + 1u == (gen + 1u) * b.nloc) {
;             __builtin_amdgcn_fence(__ATOMIC_RELEASE, "agent");
;             asm volatile("s_waitcnt vmcnt(0)" ::: "memory");
;             const unsigned og = xb_add(&bar[XB_TOP], 1u);
;             const unsigned tg = og / b.nx;
;             if (og + 1u == (tg + 1u) * b.nx) xb_add(&bar[XB_TOPGEN], 1u);
;             else XB_SPIN(xb_ld(&bar[XB_TOPGEN]) == tg, bar);
;             __builtin_amdgcn_fence(__ATOMIC_ACQUIRE, "agent");
;             xb_add(&bar[XB_XGEN(b.x)], 1u);
.Ldcv1_last:
	s_lshr_b32 s6, s3, 5
	s_and_b32 s86, s3, 31
	s_lshl_b32 s6, s6, 7
	s_add_u32 s6, s6, 0x17400000
	s_add_u32 s84, s56, s6
	s_addc_u32 s85, s57, 0
	s_waitcnt vmcnt(0)
	s_add_u32 s6, s86, 0
	s_mul_i32 s6, s6, 0x2b0000
	s_add_u32 s72, s84, s6
	s_addc_u32 s73, s85, 0
	s_add_u32 s78, s72, 0x158000
	s_addc_u32 s79, s73, 0
	ds_write2_b32 v58, v168, v169 offset1:1
	ds_write2_b32 v58, v170, v171 offset0:2 offset1:3
	ds_write2_b32 v59, v172, v173 offset1:1
	ds_write2_b32 v59, v174, v175 offset0:2 offset1:3
	ds_write2_b32 v60, v176, v177 offset1:1
	ds_write2_b32 v60, v178, v179 offset0:2 offset1:3
	ds_write2_b32 v61, v180, v181 offset1:1
	ds_write2_b32 v61, v182, v183 offset0:2 offset1:3
	s_waitcnt lgkmcnt(0)
	s_barrier
	ds_read2_b32 v[104:105], v66 offset1:129
	ds_read2_b32 v[106:107], v67 offset1:129
	ds_read2_b32 v[108:109], v68 offset1:129
	ds_read2_b32 v[110:111], v69 offset1:129
	ds_read2_b32 v[112:113], v70 offset1:129
	ds_read2_b32 v[114:115], v71 offset1:129
	ds_read2_b32 v[116:117], v72 offset1:129
	ds_read2_b32 v[118:119], v73 offset1:129
	s_waitcnt lgkmcnt(4)
	v_cvt_pk_bf16_f32 v120, v104, v105
	v_cvt_pk_bf16_f32 v121, v106, v107
	v_cvt_pk_bf16_f32 v122, v108, v109
	v_cvt_pk_bf16_f32 v123, v110, v111
	global_store_dwordx4 v57, v[120:123], s[72:73]
	s_waitcnt lgkmcnt(0)
	v_cvt_pk_bf16_f32 v124, v112, v113
	v_cvt_pk_bf16_f32 v125, v114, v115
	v_cvt_pk_bf16_f32 v126, v116, v117
	v_cvt_pk_bf16_f32 v127, v118, v119
	global_store_dwordx4 v57, v[124:127], s[78:79]
	s_add_u32 s6, s86, 1
	s_mul_i32 s6, s6, 0x2b0000
	s_add_u32 s72, s84, s6
	s_addc_u32 s73, s85, 0
	s_add_u32 s78, s72, 0x158000
	s_addc_u32 s79, s73, 0
	ds_write2_b32 v62, v184, v185 offset1:1
	ds_write2_b32 v62, v186, v187 offset0:2 offset1:3
	ds_write2_b32 v63, v188, v189 offset1:1
	ds_write2_b32 v63, v190, v191 offset0:2 offset1:3
	ds_write2_b32 v64, v192, v193 offset1:1
	ds_write2_b32 v64, v194, v195 offset0:2 offset1:3
	ds_write2_b32 v65, v196, v197 offset1:1
	ds_write2_b32 v65, v198, v199 offset0:2 offset1:3
	s_waitcnt lgkmcnt(0)
	s_barrier
	ds_read2_b32 v[104:105], v74 offset1:129
	ds_read2_b32 v[106:107], v75 offset1:129
	ds_read2_b32 v[108:109], v76 offset1:129
	ds_read2_b32 v[110:111], v77 offset1:129
	ds_read2_b32 v[112:113], v78 offset1:129
	ds_read2_b32 v[114:115], v79 offset1:129
	ds_read2_b32 v[116:117], v80 offset1:129
	ds_read2_b32 v[118:119], v81 offset1:129
	s_waitcnt lgkmcnt(4)
	v_cvt_pk_bf16_f32 v120, v104, v105
	v_cvt_pk_bf16_f32 v121, v106, v107
	v_cvt_pk_bf16_f32 v122, v108, v109
	v_cvt_pk_bf16_f32 v123, v110, v111
	global_store_dwordx4 v57, v[120:123], s[72:73]
	s_waitcnt lgkmcnt(0)
	v_cvt_pk_bf16_f32 v124, v112, v113
	v_cvt_pk_bf16_f32 v125, v114, v115
	v_cvt_pk_bf16_f32 v126, v116, v117
	v_cvt_pk_bf16_f32 v127, v118, v119
	global_store_dwordx4 v57, v[124:127], s[78:79]
	s_add_u32 s6, s86, 2
	s_mul_i32 s6, s6, 0x2b0000
	s_add_u32 s72, s84, s6
	s_addc_u32 s73, s85, 0
	s_add_u32 s78, s72, 0x158000
	s_addc_u32 s79, s73, 0
	ds_write2_b32 v58, v200, v201 offset1:1
	ds_write2_b32 v58, v202, v203 offset0:2 offset1:3
	ds_write2_b32 v59, v204, v205 offset1:1
	ds_write2_b32 v59, v206, v207 offset0:2 offset1:3
	ds_write2_b32 v60, v208, v209 offset1:1
	ds_write2_b32 v60, v210, v211 offset0:2 offset1:3
	ds_write2_b32 v61, v212, v213 offset1:1
	ds_write2_b32 v61, v214, v215 offset0:2 offset1:3
	s_waitcnt lgkmcnt(0)
	s_barrier
	ds_read2_b32 v[104:105], v66 offset1:129
	ds_read2_b32 v[106:107], v67 offset1:129
	ds_read2_b32 v[108:109], v68 offset1:129
	ds_read2_b32 v[110:111], v69 offset1:129
	ds_read2_b32 v[112:113], v70 offset1:129
	ds_read2_b32 v[114:115], v71 offset1:129
	ds_read2_b32 v[116:117], v72 offset1:129
	ds_read2_b32 v[118:119], v73 offset1:129
	s_waitcnt lgkmcnt(4)
	v_cvt_pk_bf16_f32 v120, v104, v105
	v_cvt_pk_bf16_f32 v121, v106, v107
	v_cvt_pk_bf16_f32 v122, v108, v109
	v_cvt_pk_bf16_f32 v123, v110, v111
	global_store_dwordx4 v57, v[120:123], s[72:73]
	s_waitcnt lgkmcnt(0)
	v_cvt_pk_bf16_f32 v124, v112, v113
	v_cvt_pk_bf16_f32 v125, v114, v115
	v_cvt_pk_bf16_f32 v126, v116, v117
	v_cvt_pk_bf16_f32 v127, v118, v119
	global_store_dwordx4 v57, v[124:127], s[78:79]
	s_add_u32 s6, s86, 3
	s_mul_i32 s6, s6, 0x2b0000
	s_add_u32 s72, s84, s6
	s_addc_u32 s73, s85, 0
	s_add_u32 s78, s72, 0x158000
	s_addc_u32 s79, s73, 0
	ds_write2_b32 v62, v216, v217 offset1:1
	ds_write2_b32 v62, v218, v219 offset0:2 offset1:3
	ds_write2_b32 v63, v220, v221 offset1:1
	ds_write2_b32 v63, v222, v223 offset0:2 offset1:3
	ds_write2_b32 v64, v224, v225 offset1:1
	ds_write2_b32 v64, v226, v227 offset0:2 offset1:3
	ds_write2_b32 v65, v228, v229 offset1:1
	ds_write2_b32 v65, v230, v231 offset0:2 offset1:3
	s_waitcnt lgkmcnt(0)
	s_barrier
	ds_read2_b32 v[104:105], v74 offset1:129
	ds_read2_b32 v[106:107], v75 offset1:129
	ds_read2_b32 v[108:109], v76 offset1:129
	ds_read2_b32 v[110:111], v77 offset1:129
	ds_read2_b32 v[112:113], v78 offset1:129
	ds_read2_b32 v[114:115], v79 offset1:129
	ds_read2_b32 v[116:117], v80 offset1:129
	ds_read2_b32 v[118:119], v81 offset1:129
	s_waitcnt lgkmcnt(4)
	v_cvt_pk_bf16_f32 v120, v104, v105
	v_cvt_pk_bf16_f32 v121, v106, v107
	v_cvt_pk_bf16_f32 v122, v108, v109
	v_cvt_pk_bf16_f32 v123, v110, v111
	global_store_dwordx4 v57, v[120:123], s[72:73]
	s_waitcnt lgkmcnt(0)
	v_cvt_pk_bf16_f32 v124, v112, v113
	v_cvt_pk_bf16_f32 v125, v114, v115
	v_cvt_pk_bf16_f32 v126, v116, v117
	v_cvt_pk_bf16_f32 v127, v118, v119
	global_store_dwordx4 v57, v[124:127], s[78:79]
.Ldcv1_done:
	s_waitcnt lgkmcnt(0)
	s_barrier
.LBB0_747:
	s_cmp_lt_i32 s58, 9
	s_cselect_b64 s[6:7], -1, 0
	s_cmp_gt_i32 s58, 8
	s_cselect_b64 s[4:5], -1, 0
	s_cmp_lt_i32 s59, 9
	s_cselect_b64 s[8:9], -1, 0
	s_or_b64 s[4:5], s[4:5], s[8:9]
	s_and_b64 vcc, exec, s[4:5]
	s_cbranch_vccnz .LBB0_799
	s_andn2_b64 vcc, exec, s[12:13]
	s_cbranch_vccnz .LBB0_787
	s_waitcnt vmcnt(0)
	s_waitcnt vmcnt(0)
	s_barrier
	s_and_saveexec_b64 s[4:5], s[0:1]
	s_cbranch_execz .LBB0_786
	s_mov_b64 s[8:9], exec
	v_mbcnt_lo_u32_b32 v0, s8, 0
	v_readlane_b32 s3, v255, 0
	v_mbcnt_hi_u32_b32 v0, s9, v0
	s_lshl_b32 s3, s3, 6
	s_mov_b32 s13, 0
	v_cmp_eq_u32_e32 vcc, 0, v0
	s_waitcnt vmcnt(0) expcnt(0) lgkmcnt(0)
	s_and_saveexec_b64 s[10:11], vcc
	s_cbranch_execz .LBB0_752
	s_add_i32 s12, s3, 0x500
	s_lshl_b64 s[12:13], s[12:13], 2
	s_add_u32 s12, s94, s12
	s_addc_u32 s13, s95, s13
	s_bcnt1_i32_b64 s8, s[8:9]
	v_mov_b32_e32 v1, 0
	v_mov_b32_e32 v2, s8
	global_atomic_add v1, v1, v2, s[12:13] sc0
